# v35 + 20us start stagger for blocks >= 256 in the two mix-in projection GEMM phases
# baseline (speedup 1.0000x reference)
; DEV void phase_gemm_bf16(const bf16_t* A, int lda, const bf16_t* wt, int K, int N, bf16_t* out, int ldo, char* smem) {
;   const int nct = (N + 127) >> 7;
;   int rt, ct;
;   for (int it = 0; tile_map(it, nct, rt, ct); ++it) {
;     const int r0 = rt * TM, c0 = ct * 128;
.LBB0_424:
	v_readlane_b32 s48, v250, 0
	s_nop 3
	s_cmp_lt_u32 s48, 0x100
	s_cbranch_scc1 .Lstag424
	s_sleep 127
	s_sleep 127
	s_sleep 127
	s_sleep 127
	s_sleep 127
